# + m12: W_out fused epilogue first apply loop loads the g1 gain vectors once per half (was one dependent L2 round trip per row, 16 per tile)
# speedup vs baseline: 1.0078x; 1.0026x over previous
;     __device__ __forceinline__ void fused(pg8::f32x4 (&acc)[2][2][4][2], const pg8::Unit& u, int wr, int wc, int fr, int fq, LAS unsigned char* lds, int wid, int lane) const {
;     ...
;         for (int ai = 0; ai < 2; ++ai)
; #pragma unroll
;             for (int m = 0; m < 4; ++m) { const int r = ai * 128 + wr * 64 + m * 16 + fr; const float s1 = S[r]; const size_t off = (size_t)(b * TB + u.pm * 256 + r) * D + col0;
; #pragma unroll
;                 for (int bj = 0; bj < 2; ++bj)
; #pragma unroll
;                     for (int n = 0; n < 2; ++n) { const f32x4 bs = pre[m][bj][n]; const f32x4 gg = *(const f32x4*)(g1 + col0 + bj * 128 + n * 4);
;                         acc[ai][bj][m][n] = bs + acc[ai][bj][m][n] * s1 * gg; }
;                 asm volatile("" : "+v"(acc[ai][0][m][0]), "+v"(acc[ai][0][m][1]), "+v"(acc[ai][1][m][0]), "+v"(acc[ai][1][m][1]));
;                 if (ai == 0 && m == 3) {
;                     asm volatile("" ::: "memory");
; #pragma unroll
;                     for (int m2 = 0; m2 < 4; ++m2) { const size_t off2 = (size_t)(b * TB + u.pm * 256 + 128 + wr * 64 + m2 * 16 + fr) * D + col0;
; #pragma unroll
;                         for (int bj = 0; bj < 2; ++bj)
; #pragma unroll
;                             for (int n = 0; n < 2; ++n) pre[m2][bj][n] = *(const f32x4*)(xin + off2 + bj * 128 + n * 4); }
;                 } }
.LBB0_275:
	s_or_b64 exec, exec, s[52:53]
	s_lshl_b32 s40, s82, 10
	s_ashr_i32 s41, s40, 31
	s_lshl_b64 s[58:59], s[40:41], 2
	s_add_u32 s16, s16, s58
	s_addc_u32 s17, s17, s59
	s_lshl_b32 s23, s1, 2
	s_add_i32 s23, s23, 0
	s_waitcnt lgkmcnt(0)
	s_barrier
	v_lshl_add_u32 v236, v232, 2, s23
	v_lshl_add_u64 v[218:219], v[212:213], 2, s[16:17]
	ds_read_b32 v194, v236 offset:8192
	global_load_dwordx4 v[238:241], v[218:219], off offset:16
	global_load_dwordx4 v[242:245], v[218:219], off
	global_load_dwordx4 v[202:205], v[218:219], off offset:528
	global_load_dwordx4 v[246:249], v[218:219], off offset:512
	s_add_i32 s35, s35, s1
	s_waitcnt lgkmcnt(0)
	v_pk_mul_f32 v[78:79], v[78:79], v[194:195] op_sel_hi:[1,0]
	v_pk_mul_f32 v[76:77], v[76:77], v[194:195] op_sel_hi:[1,0]
	v_pk_mul_f32 v[74:75], v[74:75], v[194:195] op_sel_hi:[1,0]
	v_pk_mul_f32 v[72:73], v[72:73], v[194:195] op_sel_hi:[1,0]
	v_pk_mul_f32 v[82:83], v[82:83], v[194:195] op_sel_hi:[1,0]
	v_pk_mul_f32 v[80:81], v[80:81], v[194:195] op_sel_hi:[1,0]
	v_pk_mul_f32 v[90:91], v[90:91], v[194:195] op_sel_hi:[1,0]
	v_pk_mul_f32 v[88:89], v[88:89], v[194:195] op_sel_hi:[1,0]
	s_waitcnt vmcnt(3)
	v_pk_fma_f32 v[74:75], v[240:241], v[74:75], v[186:187]
	s_waitcnt vmcnt(2)
	v_pk_fma_f32 v[78:79], v[244:245], v[78:79], v[190:191]
	v_pk_fma_f32 v[76:77], v[242:243], v[76:77], v[188:189]
	v_pk_fma_f32 v[72:73], v[238:239], v[72:73], v[184:185]
	s_waitcnt vmcnt(1)
	v_pk_fma_f32 v[90:91], v[90:91], v[204:205], v[178:179]
	s_waitcnt vmcnt(0)
	v_pk_fma_f32 v[82:83], v[248:249], v[82:83], v[182:183]
	v_pk_fma_f32 v[80:81], v[246:247], v[80:81], v[180:181]
	v_pk_fma_f32 v[88:89], v[88:89], v[202:203], v[176:177]
	s_nop 0
	ds_read_b32 v184, v236 offset:8256
	s_waitcnt lgkmcnt(0)
	v_pk_mul_f32 v[102:103], v[102:103], v[184:185] op_sel_hi:[1,0]
	v_pk_mul_f32 v[100:101], v[100:101], v[184:185] op_sel_hi:[1,0]
	v_pk_mul_f32 v[98:99], v[98:99], v[184:185] op_sel_hi:[1,0]
	v_pk_mul_f32 v[96:97], v[96:97], v[184:185] op_sel_hi:[1,0]
	v_pk_mul_f32 v[110:111], v[110:111], v[184:185] op_sel_hi:[1,0]
	v_pk_mul_f32 v[108:109], v[108:109], v[184:185] op_sel_hi:[1,0]
	v_pk_mul_f32 v[118:119], v[118:119], v[184:185] op_sel_hi:[1,0]
	v_pk_mul_f32 v[116:117], v[116:117], v[184:185] op_sel_hi:[1,0]
	v_pk_fma_f32 v[98:99], v[240:241], v[98:99], v[170:171]
	v_pk_fma_f32 v[102:103], v[244:245], v[102:103], v[174:175]
	v_pk_fma_f32 v[100:101], v[242:243], v[100:101], v[172:173]
	v_pk_fma_f32 v[96:97], v[238:239], v[96:97], v[168:169]
	v_pk_fma_f32 v[118:119], v[118:119], v[204:205], v[162:163]
	v_pk_fma_f32 v[110:111], v[248:249], v[110:111], v[166:167]
	v_pk_fma_f32 v[108:109], v[246:247], v[108:109], v[164:165]
	v_pk_fma_f32 v[116:117], v[116:117], v[202:203], v[160:161]
	s_nop 0
	ds_read_b32 v168, v236 offset:8320
	s_waitcnt lgkmcnt(0)
	v_pk_mul_f32 v[126:127], v[126:127], v[168:169] op_sel_hi:[1,0]
	v_pk_mul_f32 v[124:125], v[124:125], v[168:169] op_sel_hi:[1,0]
	v_pk_mul_f32 v[122:123], v[122:123], v[168:169] op_sel_hi:[1,0]
	v_pk_mul_f32 v[120:121], v[120:121], v[168:169] op_sel_hi:[1,0]
	v_pk_mul_f32 v[114:115], v[114:115], v[168:169] op_sel_hi:[1,0]
	v_pk_mul_f32 v[112:113], v[112:113], v[168:169] op_sel_hi:[1,0]
	v_pk_mul_f32 v[106:107], v[106:107], v[168:169] op_sel_hi:[1,0]
	v_pk_mul_f32 v[104:105], v[104:105], v[168:169] op_sel_hi:[1,0]
	v_pk_fma_f32 v[122:123], v[240:241], v[122:123], v[154:155]
	v_pk_fma_f32 v[126:127], v[244:245], v[126:127], v[158:159]
	v_pk_fma_f32 v[124:125], v[242:243], v[124:125], v[156:157]
	v_pk_fma_f32 v[120:121], v[238:239], v[120:121], v[152:153]
	v_pk_fma_f32 v[106:107], v[106:107], v[204:205], v[146:147]
	v_pk_fma_f32 v[114:115], v[248:249], v[114:115], v[150:151]
	v_pk_fma_f32 v[112:113], v[246:247], v[112:113], v[148:149]
	v_pk_fma_f32 v[104:105], v[104:105], v[202:203], v[144:145]
	s_nop 0
	ds_read_b32 v152, v236 offset:8384
	s_waitcnt lgkmcnt(0)
	v_pk_mul_f32 v[94:95], v[94:95], v[152:153] op_sel_hi:[1,0]
	v_pk_mul_f32 v[92:93], v[92:93], v[152:153] op_sel_hi:[1,0]
	v_pk_mul_f32 v[86:87], v[86:87], v[152:153] op_sel_hi:[1,0]
	v_pk_mul_f32 v[84:85], v[84:85], v[152:153] op_sel_hi:[1,0]
	v_pk_mul_f32 v[64:65], v[64:65], v[152:153] op_sel_hi:[1,0]
	v_pk_mul_f32 v[66:67], v[66:67], v[152:153] op_sel_hi:[1,0]
	v_pk_mul_f32 v[70:71], v[70:71], v[152:153] op_sel_hi:[1,0]
	v_pk_mul_f32 v[68:69], v[68:69], v[152:153] op_sel_hi:[1,0]
	v_pk_fma_f32 v[86:87], v[240:241], v[86:87], v[138:139]
	v_pk_fma_f32 v[94:95], v[244:245], v[94:95], v[142:143]
	v_pk_fma_f32 v[92:93], v[242:243], v[92:93], v[140:141]
	v_pk_fma_f32 v[84:85], v[238:239], v[84:85], v[136:137]
	v_pk_fma_f32 v[64:65], v[64:65], v[202:203], v[128:129]
	v_or_b32_e32 v128, s34, v232
	v_pk_fma_f32 v[66:67], v[66:67], v[204:205], v[130:131]
	v_add_u32_e32 v130, s35, v128
	v_add_u32_e32 v128, 0x90, v130
	v_ashrrev_i32_e32 v129, 31, v128
	v_pk_fma_f32 v[70:71], v[248:249], v[70:71], v[134:135]
	v_pk_fma_f32 v[68:69], v[246:247], v[68:69], v[132:133]
	v_lshlrev_b64 v[128:129], 12, v[128:129]
	v_lshl_add_u64 v[128:129], v[220:221], 0, v[128:129]
	global_load_dwordx2 v[206:207], v[218:219], off offset:512
	global_load_dwordx2 v[196:197], v[218:219], off offset:520
	global_load_dwordx4 v[168:171], v[128:129], off offset:16
	global_load_dwordx4 v[172:175], v[128:129], off
	global_load_dwordx4 v[160:163], v[128:129], off offset:528
	global_load_dwordx4 v[164:167], v[128:129], off offset:512
	v_add_u32_e32 v128, 0xa0, v130
	v_ashrrev_i32_e32 v129, 31, v128
	v_lshlrev_b64 v[128:129], 12, v[128:129]
	v_lshl_add_u64 v[128:129], v[220:221], 0, v[128:129]
	v_add_u32_e32 v176, 0x80, v130
	global_load_dwordx4 v[152:155], v[128:129], off offset:16
	global_load_dwordx4 v[156:159], v[128:129], off
	global_load_dwordx4 v[144:147], v[128:129], off offset:528
	global_load_dwordx4 v[148:151], v[128:129], off offset:512
	v_add_u32_e32 v128, 0xb0, v130
	v_ashrrev_i32_e32 v129, 31, v128
	v_ashrrev_i32_e32 v177, 31, v176
	v_lshlrev_b64 v[128:129], 12, v[128:129]
	v_lshlrev_b64 v[176:177], 12, v[176:177]
	v_lshl_add_u64 v[132:133], v[220:221], 0, v[128:129]
	v_lshl_add_u64 v[184:185], v[220:221], 0, v[176:177]
	global_load_dwordx4 v[136:139], v[132:133], off offset:16
	global_load_dwordx4 v[140:143], v[132:133], off
	global_load_dwordx4 v[128:131], v[132:133], off offset:528
	s_nop 0
	global_load_dwordx4 v[132:135], v[132:133], off offset:512
	s_nop 0
	global_load_dwordx4 v[176:179], v[184:185], off offset:528
	global_load_dwordx4 v[180:183], v[184:185], off offset:512
	global_load_dwordx4 v[186:189], v[184:185], off offset:16
	global_load_dwordx4 v[238:241], v[184:185], off
	ds_read_b32 v184, v236 offset:8704
	global_load_dwordx4 v[242:245], v[218:219], off offset:16
	global_load_dwordx4 v[246:249], v[218:219], off
	s_waitcnt lgkmcnt(0)
;     __device__ __forceinline__ void run(const pg8::f32x4 (&v)[2][2][4][2], const pg8::Unit& u, int wr, int wc, int fr, int fq, LAS unsigned char* lds, int wid, int lane) const {
;     ...
;         for (int ai = 0; ai < 2; ++ai)
; #pragma unroll
;             for (int m = 0; m < 4; ++m) {
;                 float q = 0.f;
; #pragma unroll
;                 for (int bj = 0; bj < 2; ++bj)
; #pragma unroll
;                     for (int n = 0; n < 2; ++n) { const pg8::f32x4 x = v[ai][bj][m][n]; q += (x[0] * x[0] + x[1] * x[1]) + (x[2] * x[2] + x[3] * x[3]); }
;                 q += __shfl_xor(q, 16); q += __shfl_xor(q, 32);
;                 if (fq == 0) P[(ai * 128 + wr * 64 + m * 16 + fr) * 4 + wc] = q;
;     __device__ __forceinline__ void fused(pg8::f32x4 (&acc)[2][2][4][2], const pg8::Unit& u, int wr, int wc, int fr, int fq, LAS unsigned char* lds, int wid, int lane) const {
;     ...
;         for (int ai = 0; ai < 2; ++ai)
; #pragma unroll
;             for (int m = 0; m < 4; ++m) { const int r = ai * 128 + wr * 64 + m * 16 + fr; const float s1 = S[r]; const size_t off = (size_t)(b * TB + u.pm * 256 + r) * D + col0;
; #pragma unroll
;                 for (int bj = 0; bj < 2; ++bj)
; #pragma unroll
;                     for (int n = 0; n < 2; ++n) { const f32x4 bs = pre[m][bj][n]; const f32x4 gg = *(const f32x4*)(g1 + col0 + bj * 128 + n * 4);
;                         acc[ai][bj][m][n] = bs + acc[ai][bj][m][n] * s1 * gg; }
;                 asm volatile("" : "+v"(acc[ai][0][m][0]), "+v"(acc[ai][0][m][1]), "+v"(acc[ai][1][m][0]), "+v"(acc[ai][1][m][1]));
;                 if (ai == 0 && m == 3) {
;                     asm volatile("" ::: "memory");
; #pragma unroll
;                     for (int m2 = 0; m2 < 4; ++m2) { const size_t off2 = (size_t)(b * TB + u.pm * 256 + 128 + wr * 64 + m2 * 16 + fr) * D + col0;
; #pragma unroll
;                         for (int bj = 0; bj < 2; ++bj)
; #pragma unroll
;                             for (int n = 0; n < 2; ++n) pre[m2][bj][n] = *(const f32x4*)(xin + off2 + bj * 128 + n * 4); }
;                 } }
	v_pk_mul_f32 v[62:63], v[62:63], v[184:185] op_sel_hi:[1,0]
	v_pk_mul_f32 v[60:61], v[60:61], v[184:185] op_sel_hi:[1,0]
	v_pk_mul_f32 v[58:59], v[58:59], v[184:185] op_sel_hi:[1,0]
	v_pk_mul_f32 v[56:57], v[56:57], v[184:185] op_sel_hi:[1,0]
	v_pk_mul_f32 v[54:55], v[54:55], v[184:185] op_sel_hi:[1,0]
	v_pk_mul_f32 v[52:53], v[52:53], v[184:185] op_sel_hi:[1,0]
	v_pk_mul_f32 v[50:51], v[50:51], v[184:185] op_sel_hi:[1,0]
	v_pk_mul_f32 v[48:49], v[48:49], v[184:185] op_sel_hi:[1,0]
	s_waitcnt vmcnt(1)
	v_pk_fma_f32 v[58:59], v[244:245], v[58:59], v[188:189]
	s_waitcnt vmcnt(0)
	v_pk_fma_f32 v[62:63], v[248:249], v[62:63], v[240:241]
	v_pk_fma_f32 v[60:61], v[246:247], v[60:61], v[238:239]
	v_pk_fma_f32 v[56:57], v[242:243], v[56:57], v[186:187]
	v_pk_fma_f32 v[50:51], v[50:51], v[204:205], v[178:179]
	v_pk_fma_f32 v[54:55], v[196:197], v[54:55], v[182:183]
	v_pk_fma_f32 v[52:53], v[206:207], v[52:53], v[180:181]
	v_pk_fma_f32 v[48:49], v[48:49], v[202:203], v[176:177]
	s_nop 0
	ds_read_b32 v184, v236 offset:8768
	s_waitcnt lgkmcnt(0)
	v_pk_mul_f32 v[46:47], v[46:47], v[184:185] op_sel_hi:[1,0]
	v_pk_mul_f32 v[44:45], v[44:45], v[184:185] op_sel_hi:[1,0]
	v_pk_mul_f32 v[42:43], v[42:43], v[184:185] op_sel_hi:[1,0]
	v_pk_mul_f32 v[40:41], v[40:41], v[184:185] op_sel_hi:[1,0]
	v_pk_mul_f32 v[38:39], v[38:39], v[184:185] op_sel_hi:[1,0]
	v_pk_mul_f32 v[36:37], v[36:37], v[184:185] op_sel_hi:[1,0]
	v_pk_mul_f32 v[34:35], v[34:35], v[184:185] op_sel_hi:[1,0]
	v_pk_mul_f32 v[32:33], v[32:33], v[184:185] op_sel_hi:[1,0]
	v_pk_fma_f32 v[42:43], v[244:245], v[42:43], v[170:171]
	v_pk_fma_f32 v[46:47], v[248:249], v[46:47], v[174:175]
	v_pk_fma_f32 v[44:45], v[246:247], v[44:45], v[172:173]
	v_pk_fma_f32 v[40:41], v[242:243], v[40:41], v[168:169]
	v_pk_fma_f32 v[34:35], v[34:35], v[204:205], v[162:163]
	v_pk_fma_f32 v[38:39], v[196:197], v[38:39], v[166:167]
	v_pk_fma_f32 v[36:37], v[206:207], v[36:37], v[164:165]
	v_pk_fma_f32 v[32:33], v[32:33], v[202:203], v[160:161]
	s_nop 0
	ds_read_b32 v168, v236 offset:8832
	s_waitcnt lgkmcnt(0)
	v_pk_mul_f32 v[30:31], v[30:31], v[168:169] op_sel_hi:[1,0]
	v_pk_mul_f32 v[28:29], v[28:29], v[168:169] op_sel_hi:[1,0]
	v_pk_mul_f32 v[26:27], v[26:27], v[168:169] op_sel_hi:[1,0]
	v_pk_mul_f32 v[24:25], v[24:25], v[168:169] op_sel_hi:[1,0]
	v_pk_mul_f32 v[22:23], v[22:23], v[168:169] op_sel_hi:[1,0]
	v_pk_mul_f32 v[20:21], v[20:21], v[168:169] op_sel_hi:[1,0]
	v_pk_mul_f32 v[18:19], v[18:19], v[168:169] op_sel_hi:[1,0]
	v_pk_mul_f32 v[16:17], v[16:17], v[168:169] op_sel_hi:[1,0]
	v_pk_fma_f32 v[26:27], v[244:245], v[26:27], v[154:155]
	v_pk_fma_f32 v[30:31], v[248:249], v[30:31], v[158:159]
	v_pk_fma_f32 v[28:29], v[246:247], v[28:29], v[156:157]
	v_pk_fma_f32 v[24:25], v[242:243], v[24:25], v[152:153]
	v_pk_fma_f32 v[18:19], v[18:19], v[204:205], v[146:147]
	v_pk_fma_f32 v[22:23], v[196:197], v[22:23], v[150:151]
	v_pk_fma_f32 v[20:21], v[206:207], v[20:21], v[148:149]
	v_pk_fma_f32 v[16:17], v[16:17], v[202:203], v[144:145]
	s_nop 0
	ds_read_b32 v152, v236 offset:8896
	s_waitcnt lgkmcnt(0)
	v_pk_mul_f32 v[14:15], v[14:15], v[152:153] op_sel_hi:[1,0]
	v_pk_mul_f32 v[12:13], v[12:13], v[152:153] op_sel_hi:[1,0]
	v_pk_mul_f32 v[10:11], v[10:11], v[152:153] op_sel_hi:[1,0]
	v_pk_mul_f32 v[8:9], v[8:9], v[152:153] op_sel_hi:[1,0]
	v_pk_mul_f32 v[0:1], v[0:1], v[152:153] op_sel_hi:[1,0]
	v_pk_mul_f32 v[2:3], v[2:3], v[152:153] op_sel_hi:[1,0]
	v_pk_mul_f32 v[6:7], v[6:7], v[152:153] op_sel_hi:[1,0]
	v_pk_mul_f32 v[4:5], v[4:5], v[152:153] op_sel_hi:[1,0]
	v_pk_fma_f32 v[10:11], v[244:245], v[10:11], v[138:139]
	v_pk_fma_f32 v[14:15], v[248:249], v[14:15], v[142:143]
	v_pk_fma_f32 v[12:13], v[246:247], v[12:13], v[140:141]
	v_pk_fma_f32 v[8:9], v[242:243], v[8:9], v[136:137]
	v_pk_fma_f32 v[0:1], v[0:1], v[202:203], v[128:129]
	v_mul_f32_e32 v128, v77, v77
	v_mul_f32_e32 v129, v79, v79
	v_fmac_f32_e32 v128, v76, v76
	v_fmac_f32_e32 v129, v78, v78
	v_pk_fma_f32 v[2:3], v[2:3], v[204:205], v[130:131]
	v_add_f32_e32 v128, v128, v129
	v_mul_f32_e32 v129, v73, v73
	v_mul_f32_e32 v130, v75, v75
	v_fmac_f32_e32 v129, v72, v72
	v_fmac_f32_e32 v130, v74, v74
	v_add_f32_e32 v129, v129, v130
	v_add_f32_e32 v128, v129, v128
	v_mul_f32_e32 v129, v81, v81
	v_mul_f32_e32 v130, v83, v83
	v_fmac_f32_e32 v129, v80, v80
	v_fmac_f32_e32 v130, v82, v82
	v_add_f32_e32 v129, v129, v130
	v_add_f32_e32 v128, v129, v128
	v_mul_f32_e32 v129, v89, v89
	v_mul_f32_e32 v130, v91, v91
	v_fmac_f32_e32 v129, v88, v88
	v_fmac_f32_e32 v130, v90, v90
	v_add_f32_e32 v129, v129, v130
	v_add_f32_e32 v128, v129, v128
	ds_bpermute_b32 v129, v192, v128
	v_pk_fma_f32 v[6:7], v[196:197], v[6:7], v[134:135]
	v_pk_fma_f32 v[4:5], v[206:207], v[4:5], v[132:133]
	s_waitcnt lgkmcnt(0)
	v_add_f32_e32 v128, v128, v129
	ds_bpermute_b32 v129, v233, v128
	s_and_saveexec_b64 s[16:17], s[6:7]
	s_cbranch_execz .LBB0_277
	s_lshl_b32 s1, s80, 10
	s_add_i32 s1, s0, s1
	s_waitcnt lgkmcnt(0)
	v_add_f32_e32 v128, v128, v129
	v_lshl_add_u32 v129, v232, 4, s1
	ds_write_b32 v129, v128
